# kernel start: census-rank atomic return consumed at seam 0 instead of stalling wave 0 before phase 0
# baseline (speedup 1.0000x reference)
_Z6mk_fwd4Args:
	s_load_dwordx4 s[28:31], s[0:1], 0xc0
	s_load_dwordx2 s[34:35], s[0:1], 0xd8
	s_add_u32 s4, s0, 0xd8
	v_and_b32_e32 v199, 0x3ff, v0
	s_mov_b32 s80, s2
	s_addc_u32 s5, s1, 0
	v_readfirstlane_b32 s24, v199
	v_cmp_gt_u32_e32 vcc, 64, v199
	s_and_saveexec_b64 s[6:7], vcc
	v_lshl_add_u32 v1, v199, 2, 0
	v_add_u32_e32 v1, 0x20000, v1
	v_mov_b32_e32 v2, 0
	ds_write_b32 v1, v2
	s_or_b64 exec, exec, s[6:7]
	s_load_dwordx2 s[68:69], s[0:1], 0xd0
	s_load_dword s2, s[0:1], 0xe0
	s_waitcnt lgkmcnt(0)
	s_barrier
	s_add_u32 s92, s30, 0xfc00000
	v_writelane_b32 v255, s2, 0
	s_getreg_b32 s2, hwreg(HW_REG_XCC_ID, 0, 4)
	s_addc_u32 s93, s31, 0
	s_and_b32 s33, s2, 15
	v_cmp_eq_u32_e64 s[2:3], 0, v199
	s_mov_b64 s[6:7], exec
	s_nop 0
	v_writelane_b32 v255, s2, 1
	s_nop 1
	v_writelane_b32 v255, s3, 2
	s_and_b64 s[2:3], s[6:7], s[2:3]
	s_mov_b64 exec, s[2:3]
	s_cbranch_execz .LBB0_6
	s_mov_b64 s[10:11], exec
	v_mbcnt_lo_u32_b32 v1, s10, 0
	v_mbcnt_hi_u32_b32 v1, s11, v1
	v_cmp_eq_u32_e32 vcc, 0, v1
	s_and_saveexec_b64 s[8:9], vcc
	s_cbranch_execz .LBB0_5
	s_lshl_b32 s2, s33, 8
	s_bcnt1_i32_b64 s3, s[10:11]
	v_mov_b32_e32 v2, s2
	v_mov_b32_e32 v3, s3
	global_atomic_add v150, v2, v3, s[92:93] offset:1024 sc0
.LBB0_5:
	s_or_b64 exec, exec, s[8:9]
.LBB0_6:
	s_or_b64 exec, exec, s[6:7]
	s_load_dwordx16 s[52:67], s[0:1], 0x0
	s_load_dwordx16 s[36:51], s[0:1], 0x40
	s_load_dwordx16 s[8:23], s[0:1], 0x80
	s_cmpk_lt_i32 s69, 0x3e9
	s_waitcnt lgkmcnt(0)
	v_writelane_b32 v255, s8, 3
	s_nop 1
	v_writelane_b32 v255, s9, 4
	v_writelane_b32 v255, s10, 5
	v_writelane_b32 v255, s11, 6
	v_writelane_b32 v255, s12, 7
	v_writelane_b32 v255, s13, 8
	v_writelane_b32 v255, s14, 9
	v_writelane_b32 v255, s15, 10
	v_writelane_b32 v255, s16, 11
	v_writelane_b32 v255, s17, 12
	v_writelane_b32 v255, s18, 13
	v_writelane_b32 v255, s19, 14
	v_writelane_b32 v255, s20, 15
	v_writelane_b32 v255, s21, 16
	v_writelane_b32 v255, s22, 17
	v_writelane_b32 v255, s23, 18
	s_cbranch_scc1 .LBB0_18
	v_lshrrev_b32_e32 v1, 20, v0
	v_lshrrev_b32_e32 v0, 10, v0
	v_or_b32_e32 v0, v0, v1
	s_movk_i32 s0, 0x3ff
	v_and_or_b32 v0, v0, s0, v199
	v_cmp_eq_u32_e32 vcc, 0, v0
	s_barrier
	s_and_saveexec_b64 s[0:1], vcc
	s_cbranch_execz .LBB0_17
	buffer_wbl2 sc1
	s_load_dwordx2 s[4:5], s[4:5], 0x58
	v_mov_b32_e32 v2, 0
	s_mov_b64 s[6:7], exec
	v_mbcnt_lo_u32_b32 v1, s6, 0
	v_mbcnt_hi_u32_b32 v1, s7, v1
	s_waitcnt lgkmcnt(0)
	global_load_dword v0, v2, s[4:5] offset:40
	v_cmp_eq_u32_e32 vcc, 0, v1
	s_and_saveexec_b64 s[8:9], vcc
	s_cbranch_execz .LBB0_10
	s_bcnt1_i32_b64 s2, s[6:7]
	v_mov_b32_e32 v3, s2
	global_atomic_add v3, v2, v3, s[4:5] offset:32 sc0

.LBB0_42:
	s_cmp_gt_i32 s69, 1
	s_cselect_b64 s[0:1], -1, 0
	s_and_b64 s[4:5], s[6:7], s[0:1]
	s_andn2_b64 vcc, exec, s[4:5]
	v_mov_b32_e32 v0, s80
	s_cbranch_vccnz .LBB0_108
	s_waitcnt vmcnt(0)
	s_barrier
	s_mov_b64 s[4:5], exec
	v_readlane_b32 s6, v255, 1
	v_readlane_b32 s7, v255, 2
	s_and_b64 s[6:7], s[4:5], s[6:7]
	s_mov_b64 exec, s[6:7]
	s_cbranch_execz .LBB0_95
	s_add_i32 s3, 0, 0x20040
	v_mov_b32_e32 v0, s3
	s_waitcnt vmcnt(0) expcnt(0) lgkmcnt(0)
	ds_write_b32 v0, v150 offset:8
	ds_read_b32 v2, v0
	s_add_i32 s3, 0, 0x20044
	v_mov_b32_e32 v0, s3
	ds_read_b32 v0, v0
	s_waitcnt lgkmcnt(1)
	v_cmp_ne_u32_e32 vcc, 0, v2
	s_cbranch_vccnz .LBB0_59
	s_add_u32 s6, s30, 0xfc00200
	s_addc_u32 s7, s31, 0
	s_add_u32 s8, s30, 0xfc00400
	s_addc_u32 s9, s31, 0
	s_add_u32 s38, s30, 0xfc00500
	s_addc_u32 s39, s31, 0
	s_add_u32 s40, s30, 0xfc00600
	s_addc_u32 s41, s31, 0
	s_add_u32 s44, s30, 0xfc00700
	s_addc_u32 s45, s31, 0
	s_add_u32 s60, s30, 0xfc00800
	s_addc_u32 s61, s31, 0
	s_add_u32 s62, s30, 0xfc00900
	s_addc_u32 s63, s31, 0
	s_add_u32 s64, s30, 0xfc00a00
	s_addc_u32 s65, s31, 0
	s_add_u32 s66, s30, 0xfc00b00
	s_addc_u32 s67, s31, 0
	s_add_u32 s76, s30, 0xfc00c00
	s_addc_u32 s77, s31, 0
	s_add_u32 s78, s30, 0xfc00d00
	s_addc_u32 s79, s31, 0
	s_mov_b32 s14, s80
	s_add_u32 s80, s30, 0xfc00e00
	s_addc_u32 s81, s31, 0
	s_add_u32 s82, s30, 0xfc00f00
	s_addc_u32 s83, s31, 0
	s_add_u32 s84, s30, 0xfc01000
	s_addc_u32 s85, s31, 0
	s_add_u32 s86, s30, 0xfc01100
	s_addc_u32 s87, s31, 0
	s_add_u32 s88, s30, 0xfc01200
	v_readlane_b32 s3, v255, 0
	s_addc_u32 s89, s31, 0
	s_mul_i32 s3, s35, s3
	s_add_u32 s90, s30, 0xfc01300
	s_mov_b64 s[12:13], s[92:93]
	s_mul_i32 s3, s3, s34
	s_addc_u32 s91, s31, 0
	s_mov_b32 s70, 1
	v_mov_b32_e32 v16, 0
	s_branch .LBB0_47
